# v12: hoisted residual-tile loads + de-serialized census and final sum-of-squares loads
# speedup vs baseline: 1.0077x; 1.0071x over previous
;     __device__ __forceinline__ void fused(f32x4 (&acc)[2][2][4][2], const Unit& u, int wr, int wc, int fr, int fq, PG8_LAS unsigned char* lds, int wid, int lane) const {
;     ...
;         if (tid < 256) { float sq = 0.f;
; #pragma unroll
;             for (int t = 0; t < 8; ++t) sq += __hip_atomic_load(ss + (size_t)(u.pm * BM + tid) * 8 + t, __ATOMIC_RELAXED, __HIP_MEMORY_SCOPE_AGENT);
;             tbl[tid] = 1.0f / sqrtf(sq * (1.0f / 2048.0f) + 1e-6f); }
.LBB0_332:
	s_or_b64 exec, exec, s[0:1]
	s_waitcnt vmcnt(0) lgkmcnt(0)
	s_barrier
	s_and_saveexec_b64 s[4:5], s[2:3]
	s_cbranch_execz .LBB0_334
	v_lshlrev_b64 v[2:3], 5, v[2:3]
	v_lshl_add_u64 v[2:3], s[28:29], 0, v[2:3]
	global_load_dword v137, v[2:3], off sc1
	global_load_dword v138, v[2:3], off offset:4 sc1
	global_load_dword v156, v[2:3], off offset:8 sc1
	global_load_dword v157, v[2:3], off offset:12 sc1
	global_load_dword v158, v[2:3], off offset:16 sc1
	global_load_dword v159, v[2:3], off offset:20 sc1
	global_load_dword v160, v[2:3], off offset:24 sc1
	global_load_dword v161, v[2:3], off offset:28 sc1
	s_mov_b32 s0, 0xf800000
	s_waitcnt vmcnt(0)
	v_add_f32_e32 v137, 0, v137
	v_add_f32_e32 v137, v137, v138
	v_add_f32_e32 v137, v137, v156
	v_add_f32_e32 v137, v137, v157
	v_add_f32_e32 v137, v137, v158
	v_add_f32_e32 v137, v137, v159
	v_add_f32_e32 v137, v137, v160
	v_add_f32_e32 v2, v137, v161
	v_fmamk_f32 v2, v2, 0x3a000000, v210
	v_cmp_gt_f32_e32 vcc, s0, v2
	v_mul_f32_e32 v3, 0x4f800000, v2
	s_nop 0
	v_cndmask_b32_e32 v2, v2, v3, vcc
	v_sqrt_f32_e32 v3, v2
	s_nop 0
	v_add_u32_e32 v137, -1, v3
	v_fma_f32 v138, -v137, v3, v2
	v_cmp_ge_f32_e64 s[0:1], 0, v138
	v_add_u32_e32 v138, 1, v3
	s_nop 0
	v_cndmask_b32_e64 v137, v3, v137, s[0:1]
	v_fma_f32 v3, -v138, v3, v2
	v_cmp_lt_f32_e64 s[0:1], 0, v3
	s_nop 1
	v_cndmask_b32_e64 v3, v137, v138, s[0:1]
	v_mul_f32_e32 v137, 0x37800000, v3
	v_cndmask_b32_e32 v3, v3, v137, vcc
	v_cmp_class_f32_e32 vcc, v2, v211
	s_nop 1
	v_cndmask_b32_e32 v2, v3, v2, vcc
	v_div_scale_f32 v3, s[0:1], v2, v2, 1.0
	v_rcp_f32_e32 v137, v3
	s_nop 0
	v_fma_f32 v138, -v3, v137, 1.0
	v_fmac_f32_e32 v137, v138, v137
	v_div_scale_f32 v138, vcc, 1.0, v2, 1.0
	v_mul_f32_e32 v139, v138, v137
	v_fma_f32 v141, -v3, v139, v138
	v_fmac_f32_e32 v139, v141, v137
	v_fma_f32 v3, -v3, v139, v138
	v_div_fmas_f32 v3, v3, v137, v139
	v_div_fixup_f32 v2, v3, v2, 1.0
	v_lshl_add_u32 v3, v136, 2, 0
	ds_write_b32 v3, v2 offset:4096

; __device__ __forceinline__ unsigned xb_ld(unsigned* p)              { return __hip_atomic_load(p, __ATOMIC_RELAXED, __HIP_MEMORY_SCOPE_AGENT); }
; __device__ __forceinline__ void xcd_barrier_complete(unsigned* bar, unsigned x, unsigned& nloc, unsigned& nx) {
;     ...
;     for (;;) {
;         sum = 0u; cnt = 0u; mine = 0u;
; #pragma unroll
;         for (unsigned j = 0; j < 16; ++j) { const unsigned c = xb_ld(&bar[XB_XCNT(j)]); sum += c; cnt += (c > 0u) ? 1u : 0u; mine = (j == x) ? c : mine; }
;         if (sum == G) break;
.LBB0_614:
	v_readlane_b32 s2, v250, 37
	v_readlane_b32 s3, v250, 38
	v_readlane_b32 s4, v250, 32
	s_nop 4
	global_load_dword v0, v1, s[2:3] sc1
	v_readlane_b32 s2, v250, 39
	v_readlane_b32 s3, v250, 40
	s_waitcnt lgkmcnt(0)
	s_nop 4
	global_load_dword v2, v1, s[2:3] sc1
	v_readlane_b32 s2, v250, 41
	v_readlane_b32 s3, v250, 42
	s_nop 4
	global_load_dword v3, v1, s[2:3] sc1
	v_readlane_b32 s2, v250, 43
	v_readlane_b32 s3, v250, 44
	s_nop 4
	global_load_dword v8, v1, s[2:3] sc1
	v_readlane_b32 s2, v250, 45
	v_readlane_b32 s3, v250, 46
	s_nop 4
	global_load_dword v9, v1, s[2:3] sc1
	v_readlane_b32 s2, v250, 47
	v_readlane_b32 s3, v250, 48
	s_nop 4
	global_load_dword v10, v1, s[2:3] sc1
	v_readlane_b32 s2, v250, 49
	v_readlane_b32 s3, v250, 50
	s_nop 4
	global_load_dword v11, v1, s[2:3] sc1
	v_readlane_b32 s2, v250, 51
	v_readlane_b32 s3, v250, 52
	s_nop 4
	global_load_dword v12, v1, s[2:3] sc1
	v_readlane_b32 s2, v250, 53
	v_readlane_b32 s3, v250, 54
	s_nop 4
	global_load_dword v13, v1, s[2:3] sc1
	v_readlane_b32 s2, v250, 55
	v_readlane_b32 s3, v250, 56
	s_nop 4
	global_load_dword v14, v1, s[2:3] sc1
	v_readlane_b32 s2, v250, 57
	v_readlane_b32 s3, v250, 58
	s_nop 4
	global_load_dword v15, v1, s[2:3] sc1
	v_readlane_b32 s2, v250, 59
	v_readlane_b32 s3, v250, 60
	s_nop 4
	global_load_dword v16, v1, s[2:3] sc1
	v_readlane_b32 s2, v250, 61
	v_readlane_b32 s3, v250, 62
	s_nop 4
	global_load_dword v17, v1, s[2:3] sc1
	v_readlane_b32 s2, v250, 63
	v_readlane_b32 s3, v251, 0
	s_nop 4
	global_load_dword v18, v1, s[2:3] sc1
	v_readlane_b32 s2, v251, 1
	v_readlane_b32 s3, v251, 2
	s_nop 4
	global_load_dword v19, v1, s[2:3] sc1
	v_readlane_b32 s2, v251, 3
	v_readlane_b32 s3, v251, 4
	s_nop 4
	global_load_dword v20, v1, s[2:3] sc1
	s_mov_b64 s[2:3], -1
	s_waitcnt vmcnt(0)
	v_add_u32_e32 v21, v2, v0
	v_add_u32_e32 v21, v21, v3
	v_add_u32_e32 v21, v21, v8
	v_add_u32_e32 v21, v21, v9
	v_add_u32_e32 v21, v21, v10
	v_add_u32_e32 v21, v21, v11
	v_add_u32_e32 v21, v21, v12
	v_add_u32_e32 v21, v21, v13
	v_add_u32_e32 v21, v21, v14
	v_add_u32_e32 v21, v21, v15
	v_add_u32_e32 v21, v21, v16
	v_add_u32_e32 v21, v21, v17
	v_add_u32_e32 v21, v21, v18
	v_add_u32_e32 v21, v21, v19
	v_add_u32_e32 v21, v21, v20
	v_cmp_eq_u32_e32 vcc, s4, v21
	s_mov_b64 s[4:5], -1
	s_cbranch_vccnz .LBB0_613
	s_and_b32 s2, s10, 0xff
	s_cmp_eq_u32 s2, 0
	s_mov_b64 s[2:3], -1
	s_mov_b64 s[6:7], -1
	s_sleep 1
	s_cbranch_scc1 .LBB0_618
	s_and_b64 vcc, exec, s[6:7]
	s_cbranch_vccz .LBB0_613
